# norm loops: invariant gain/scale/shift loaded once (first iteration), guarded next-rows touch
# baseline (speedup 1.0000x reference)
; __device__ __forceinline__ void unpack8(const v4u& w, float (&f)[8]) { f[0] = bflo(w.x); f[1] = bfhi(w.x); f[2] = bflo(w.y); f[3] = bfhi(w.y); f[4] = bflo(w.z); f[5] = bfhi(w.z); f[6] = bflo(w.w); f[7] = bfhi(w.w); }
; template <bool ZP, bool XF32, bool OUT8 = false>
; __device__ __forceinline__ void norm_phase(LAS unsigned char* lds, const void* xin, const float* gain, const float* sh, const float* sc, bf16* hout, const float* wzt, float* zout, int lane, int wave, int vcu, int G) {
;     ...
;     for (int it_ = 0; it_ < nit; ++it_) {
;         const int m0 = xdeal ? 2048 * (gw >> 8) + 2 * (gw & 255) + 512 * it_ : 2 * gw + it_ * 2 * NGW;
;         if (m0 >= M) break;
;         f32x4 v[2][4][2]; float ss[2] = {0.f, 0.f};
; #pragma unroll
;         for (int r = 0; r < 2; ++r)
; #pragma unroll
;             for (int j = 0; j < 4; ++j) {
;                 if constexpr (XF32) { const float* xr = (const float*)xin + (size_t)(m0 + r) * D + 8 * lane; v[r][j][0] = *(const f32x4*)(xr + 512 * j); v[r][j][1] = *(const f32x4*)(xr + 512 * j + 4); }
;                 else { float f[8]; unpack8(*(const v4u*)((const bf16*)xin + (size_t)(m0 + r) * D + 8 * lane + 512 * j), f); v[r][j][0] = (f32x4){f[0], f[1], f[2], f[3]}; v[r][j][1] = (f32x4){f[4], f[5], f[6], f[7]}; } }
; #pragma unroll
;         for (int r = 0; r < 2; ++r)
; #pragma unroll
;             for (int j = 0; j < 4; ++j)
; #pragma unroll
;                 for (int e = 0; e < 4; ++e) ss[r] += v[r][j][0][e] * v[r][j][0][e] + v[r][j][1][e] * v[r][j][1][e];
; #pragma unroll
;         for (int r = 0; r < 2; ++r) { const int m = m0 + r, b = m >> 11;
;             const float rstd = rsqrtf(wave_sum(ss[r]) * (1.0f / D) + EPS);
; #pragma unroll
;             for (int j = 0; j < 4; ++j) { const int col = 512 * j + 8 * lane;
; #pragma unroll
;                 for (int q = 0; q < 2; ++q) { const f32x4 gg = *(const f32x4*)(gain + col + 4 * q), s1 = *(const f32x4*)(sc + (size_t)b * MODW + col + 4 * q), s0 = *(const f32x4*)(sh + (size_t)b * MODW + col + 4 * q);
;                     v[r][j][q] = (v[r][j][q] * rstd * gg) * (s1 + 1.0f) + s0; }
.LBB0_682:
	s_ashr_i32 s15, s14, 31
	s_add_i32 s10, s14, 1
	s_lshl_b64 s[12:13], s[14:15], 12
	s_ashr_i32 s11, s10, 31
	v_lshl_add_u64 v[2:3], v[6:7], 0, s[12:13]
	v_lshl_add_u64 v[244:245], v[2:3], 0, s[100:101]
	s_lshl_b64 s[8:9], s[10:11], 12
	global_load_dwordx4 v[18:21], v[2:3], off offset:1024
	global_load_dwordx4 v[22:25], v[2:3], off offset:3072
	global_load_dwordx4 v[32:35], v[2:3], off
	global_load_dwordx4 v[38:41], v[2:3], off offset:2048
	v_lshl_add_u64 v[26:27], v[6:7], 0, s[8:9]
	v_lshl_add_u64 v[246:247], v[26:27], 0, s[100:101]
	global_load_dwordx4 v[78:81], v[26:27], off offset:1024
	global_load_dwordx4 v[92:95], v[26:27], off
	global_load_dwordx4 v[2:5], v[26:27], off offset:3072
	global_load_dwordx4 v[96:99], v[26:27], off offset:2048
	s_ashr_i32 s0, s14, 11
	s_mul_hi_i32 s1, s0, 0xc000
	s_mul_i32 s0, s0, 0xc000
	s_add_u32 s14, s19, s0
	s_addc_u32 s15, s20, s1
	s_add_u32 s16, s7, s0
	s_addc_u32 s17, s18, s1
	v_cmp_lt_i32_e32 vcc, v86, v85
	s_ashr_i32 s0, s10, 11
	s_mul_hi_i32 s1, s0, 0xc000
	v_cndmask_b32_e32 v82, v84, v86, vcc
	v_lshlrev_b32_e32 v82, 2, v82
	v_cmp_lt_i32_e32 vcc, v87, v85
	s_mul_i32 s0, s0, 0xc000
	s_add_u32 s10, s19, s0
	s_addc_u32 s11, s20, s1
	s_waitcnt vmcnt(0)
	v_lshlrev_b32_e32 v45, 16, v20
	v_lshlrev_b32_e32 v43, 16, v18
	v_lshlrev_b32_e32 v57, 16, v34
	v_and_b32_e32 v61, 0xffff0000, v34
	v_lshlrev_b32_e32 v56, 16, v94
	v_and_b32_e32 v60, 0xffff0000, v94
	v_lshlrev_b32_e32 v55, 16, v32
	v_and_b32_e32 v59, 0xffff0000, v32
	v_lshlrev_b32_e32 v63, 16, v35
	v_and_b32_e32 v26, 0xffff0000, v78
	v_and_b32_e32 v30, 0xffff0000, v80
	v_lshlrev_b32_e32 v54, 16, v92
	v_and_b32_e32 v58, 0xffff0000, v92
	v_lshlrev_b32_e32 v62, 16, v95
	v_lshlrev_b32_e32 v42, 16, v78
	v_lshlrev_b32_e32 v44, 16, v80
	v_lshlrev_b32_e32 v46, 16, v79
	v_and_b32_e32 v48, 0xffff0000, v79
	v_lshlrev_b32_e32 v50, 16, v81
	v_and_b32_e32 v52, 0xffff0000, v81
	v_pk_mul_f32 v[78:79], v[56:57], v[56:57]
	v_pk_mul_f32 v[80:81], v[60:61], v[60:61]
	v_lshlrev_b32_e32 v65, 16, v33
	v_and_b32_e32 v69, 0xffff0000, v35
	v_lshlrev_b32_e32 v64, 16, v93
	v_and_b32_e32 v66, 0xffff0000, v93
	v_and_b32_e32 v68, 0xffff0000, v95
	v_pk_mul_f32 v[92:93], v[62:63], v[62:63]
	v_pk_fma_f32 v[78:79], v[54:55], v[54:55], v[78:79]
	v_pk_fma_f32 v[80:81], v[58:59], v[58:59], v[80:81]
	v_and_b32_e32 v67, 0xffff0000, v33
	v_pk_mul_f32 v[94:95], v[68:69], v[68:69]
	v_pk_fma_f32 v[92:93], v[64:65], v[64:65], v[92:93]
	v_pk_add_f32 v[78:79], v[78:79], v[80:81]
	v_pk_fma_f32 v[80:81], v[66:67], v[66:67], v[94:95]
	v_pk_add_f32 v[78:79], v[92:93], v[78:79]
	v_and_b32_e32 v31, 0xffff0000, v20
	v_pk_add_f32 v[78:79], v[80:81], v[78:79]
	v_pk_mul_f32 v[80:81], v[44:45], v[44:45]
	v_and_b32_e32 v27, 0xffff0000, v18
	v_pk_fma_f32 v[80:81], v[42:43], v[42:43], v[80:81]
	v_lshlrev_b32_e32 v51, 16, v21
	v_pk_add_f32 v[78:79], v[80:81], v[78:79]
	v_pk_mul_f32 v[80:81], v[30:31], v[30:31]
	v_lshlrev_b32_e32 v47, 16, v19
	v_pk_fma_f32 v[80:81], v[26:27], v[26:27], v[80:81]
	v_and_b32_e32 v49, 0xffff0000, v19
	v_and_b32_e32 v18, 0xffff0000, v4
	v_lshlrev_b32_e32 v19, 16, v4
	v_pk_add_f32 v[78:79], v[80:81], v[78:79]
	v_pk_mul_f32 v[80:81], v[50:51], v[50:51]
	v_and_b32_e32 v70, 0xffff0000, v22
	v_lshlrev_b32_e32 v71, 16, v22
	v_and_b32_e32 v72, 0xffff0000, v24
	v_lshlrev_b32_e32 v73, 16, v24
	v_and_b32_e32 v53, 0xffff0000, v21
	v_and_b32_e32 v20, 0xffff0000, v2
	v_lshlrev_b32_e32 v21, 16, v2
	v_lshlrev_b32_e32 v22, 16, v96
	v_and_b32_e32 v24, 0xffff0000, v96
	v_lshlrev_b32_e32 v28, 16, v97
	v_and_b32_e32 v32, 0xffff0000, v97
	v_pk_mul_f32 v[96:97], v[18:19], v[18:19]
	v_pk_fma_f32 v[80:81], v[46:47], v[46:47], v[80:81]
	v_pk_fma_f32 v[116:117], v[20:21], v[20:21], v[96:97]
	v_pk_add_f32 v[96:97], v[80:81], v[78:79]
	s_cmp_lg_u32 s24, 0
	s_cbranch_scc1 .Lnorm_once_LBB0_679
	global_load_dwordx4 v[128:131], v1, s[14:15] offset:16
	global_load_dwordx4 v[132:135], v1, s[14:15]
	global_load_dwordx4 v[136:139], v[8:9], off offset:16
	global_load_dwordx4 v[140:143], v[8:9], off
	global_load_dwordx4 v[144:147], v1, s[16:17] offset:16
	global_load_dwordx4 v[148:151], v1, s[16:17]
	global_load_dwordx4 v[152:155], v[8:9], off offset:2048
	global_load_dwordx4 v[156:159], v1, s[14:15] offset:2048
	global_load_dwordx4 v[160:163], v1, s[16:17] offset:2048
	global_load_dwordx4 v[164:167], v[8:9], off offset:2064
	global_load_dwordx4 v[168:171], v1, s[14:15] offset:2064
	global_load_dwordx4 v[172:175], v1, s[16:17] offset:2064
	global_load_dwordx4 v[176:179], v[10:11], off
	global_load_dwordx4 v[180:183], v17, s[14:15]
	global_load_dwordx4 v[184:187], v[10:11], off offset:16
	global_load_dwordx4 v[188:191], v17, s[14:15] offset:16
	global_load_dwordx4 v[192:195], v17, s[16:17]
	global_load_dwordx4 v[196:199], v17, s[16:17] offset:16
	global_load_dwordx4 v[200:203], v[12:13], off
	global_load_dwordx4 v[204:207], v83, s[14:15]
	global_load_dwordx4 v[208:211], v[12:13], off offset:16
	global_load_dwordx4 v[212:215], v83, s[14:15] offset:16
	global_load_dwordx4 v[216:219], v83, s[16:17]
	global_load_dwordx4 v[220:223], v83, s[16:17] offset:16
; template <bool ZP, bool XF32, bool OUT8 = false>
; __device__ __forceinline__ void norm_phase(LAS unsigned char* lds, const void* xin, const float* gain, const float* sh, const float* sc, bf16* hout, const float* wzt, float* zout, int lane, int wave, int vcu, int G) {
;     ...
;                 for (int e = 0; e < 4; ++e) ss[r] += v[r][j][0][e] * v[r][j][0][e] + v[r][j][1][e] * v[r][j][1][e];
; #pragma unroll
;         for (int r = 0; r < 2; ++r) { const int m = m0 + r, b = m >> 11;
;             const float rstd = rsqrtf(wave_sum(ss[r]) * (1.0f / D) + EPS);
; #pragma unroll
;             for (int j = 0; j < 4; ++j) { const int col = 512 * j + 8 * lane;
; #pragma unroll
;                 for (int q = 0; q < 2; ++q) { const f32x4 gg = *(const f32x4*)(gain + col + 4 * q), s1 = *(const f32x4*)(sc + (size_t)b * MODW + col + 4 * q), s0 = *(const f32x4*)(sh + (size_t)b * MODW + col + 4 * q);
.Lnorm_once_LBB0_679:
	v_and_b32_e32 v74, 0xffff0000, v23
	v_lshlrev_b32_e32 v75, 16, v23
	v_and_b32_e32 v76, 0xffff0000, v25
	v_lshlrev_b32_e32 v77, 16, v25
	v_lshlrev_b32_e32 v23, 16, v38
	v_and_b32_e32 v25, 0xffff0000, v38
	v_lshlrev_b32_e32 v35, 16, v40
	v_and_b32_e32 v37, 0xffff0000, v40
	v_lshlrev_b32_e32 v34, 16, v98
	v_and_b32_e32 v36, 0xffff0000, v98
	v_lshlrev_b32_e32 v38, 16, v99
	v_and_b32_e32 v40, 0xffff0000, v99
	v_pk_mul_f32 v[98:99], v[52:53], v[52:53]
	v_lshlrev_b32_e32 v29, 16, v39
	v_pk_fma_f32 v[98:99], v[48:49], v[48:49], v[98:99]
	v_and_b32_e32 v33, 0xffff0000, v39
	v_pk_add_f32 v[96:97], v[98:99], v[96:97]
	v_pk_mul_f32 v[98:99], v[34:35], v[34:35]
	v_lshlrev_b32_e32 v39, 16, v41
	v_pk_fma_f32 v[98:99], v[22:23], v[22:23], v[98:99]
	v_and_b32_e32 v41, 0xffff0000, v41
	v_pk_add_f32 v[96:97], v[98:99], v[96:97]
	v_pk_mul_f32 v[98:99], v[36:37], v[36:37]
	v_pk_mul_f32 v[100:101], v[72:73], v[72:73]
	v_pk_fma_f32 v[98:99], v[24:25], v[24:25], v[98:99]
	v_pk_mul_f32 v[102:103], v[76:77], v[76:77]
	v_pk_add_f32 v[96:97], v[98:99], v[96:97]
	v_pk_mul_f32 v[98:99], v[38:39], v[38:39]
	v_pk_fma_f32 v[112:113], v[70:71], v[70:71], v[100:101]
	v_pk_fma_f32 v[98:99], v[28:29], v[28:29], v[98:99]
	v_pk_fma_f32 v[114:115], v[74:75], v[74:75], v[102:103]
	v_pk_add_f32 v[96:97], v[98:99], v[96:97]
	v_pk_mul_f32 v[98:99], v[40:41], v[40:41]
	v_mov_b32_e32 v120, v117
	v_pk_fma_f32 v[98:99], v[32:33], v[32:33], v[98:99]
	v_mov_b32_e32 v121, v113
	v_pk_add_f32 v[118:119], v[98:99], v[96:97]
	v_and_b32_e32 v4, 0xffff0000, v5
	v_lshlrev_b32_e32 v5, 16, v5
	v_pk_add_f32 v[118:119], v[120:121], v[118:119]
	v_and_b32_e32 v2, 0xffff0000, v3
	v_lshlrev_b32_e32 v3, 16, v3
	v_pk_mul_f32 v[120:121], v[4:5], v[4:5]
	v_mov_b32_e32 v117, v112
	v_pk_fma_f32 v[120:121], v[2:3], v[2:3], v[120:121]
	v_pk_add_f32 v[112:113], v[116:117], v[118:119]
	v_mov_b32_e32 v116, v121
	v_mov_b32_e32 v117, v115
	v_pk_add_f32 v[112:113], v[116:117], v[112:113]
	v_mov_b32_e32 v121, v114
	v_pk_add_f32 v[112:113], v[120:121], v[112:113]
	ds_bpermute_b32 v115, v82, v113
	ds_bpermute_b32 v114, v82, v112
	v_cndmask_b32_e32 v82, v84, v87, vcc
	v_lshlrev_b32_e32 v82, 2, v82
	v_cmp_lt_i32_e32 vcc, v88, v85
	v_mov_b32_e32 v122, v35
	s_waitcnt lgkmcnt(0)
	v_pk_add_f32 v[112:113], v[112:113], v[114:115]
	ds_bpermute_b32 v115, v82, v113
	ds_bpermute_b32 v114, v82, v112
	v_cndmask_b32_e32 v82, v84, v88, vcc
	v_lshlrev_b32_e32 v82, 2, v82
	v_cmp_lt_i32_e32 vcc, v89, v85
	v_mov_b32_e32 v123, v37
	s_waitcnt lgkmcnt(0)
	v_pk_add_f32 v[112:113], v[112:113], v[114:115]
	ds_bpermute_b32 v115, v82, v113
	ds_bpermute_b32 v114, v82, v112
	v_cndmask_b32_e32 v82, v84, v89, vcc
	v_lshlrev_b32_e32 v82, 2, v82
	v_cmp_lt_i32_e32 vcc, v90, v85
	v_mov_b32_e32 v120, v39
	s_waitcnt lgkmcnt(0)
	v_pk_add_f32 v[112:113], v[112:113], v[114:115]
	ds_bpermute_b32 v115, v82, v113
	ds_bpermute_b32 v114, v82, v112
	v_cndmask_b32_e32 v82, v84, v90, vcc
	v_lshlrev_b32_e32 v82, 2, v82
	v_cmp_lt_i32_e32 vcc, v91, v85
	s_waitcnt vmcnt(0)
	v_mov_b64_e32 v[92:93], v[128:129]
	v_mov_b64_e32 v[94:95], v[130:131]
	v_mov_b64_e32 v[78:79], v[132:133]
	v_mov_b64_e32 v[80:81], v[134:135]
	v_mov_b64_e32 v[96:97], v[136:137]
	v_mov_b64_e32 v[98:99], v[138:139]
	v_mov_b64_e32 v[100:101], v[140:141]
	v_mov_b64_e32 v[102:103], v[142:143]
	v_mov_b64_e32 v[104:105], v[144:145]
	v_mov_b64_e32 v[106:107], v[146:147]
	v_mov_b64_e32 v[108:109], v[148:149]
	v_mov_b64_e32 v[110:111], v[150:151]
	s_cmp_lg_u32 s3, 1
	s_cbranch_scc0 .Lnorm_nt_LBB0_679
	global_load_dwordx4 v[248:251], v[244:245], off offset:1024
	global_load_dwordx4 v[248:251], v[244:245], off offset:3072
	global_load_dwordx4 v[248:251], v[244:245], off
	global_load_dwordx4 v[248:251], v[244:245], off offset:2048
	global_load_dwordx4 v[248:251], v[246:247], off offset:1024
	global_load_dwordx4 v[248:251], v[246:247], off
	global_load_dwordx4 v[248:251], v[246:247], off offset:3072
	global_load_dwordx4 v[248:251], v[246:247], off offset:2048

; __device__ __forceinline__ void unpack8(const v4u& w, float (&f)[8]) { f[0] = bflo(w.x); f[1] = bfhi(w.x); f[2] = bflo(w.y); f[3] = bfhi(w.y); f[4] = bflo(w.z); f[5] = bfhi(w.z); f[6] = bflo(w.w); f[7] = bfhi(w.w); }
; template <bool ZP, bool XF32, bool OUT8 = false>
; __device__ __forceinline__ void norm_phase(LAS unsigned char* lds, const void* xin, const float* gain, const float* sh, const float* sc, bf16* hout, const float* wzt, float* zout, int lane, int wave, int vcu, int G) {
;     ...
;     for (int it_ = 0; it_ < nit; ++it_) {
;         const int m0 = xdeal ? 2048 * (gw >> 8) + 2 * (gw & 255) + 512 * it_ : 2 * gw + it_ * 2 * NGW;
;         if (m0 >= M) break;
;         f32x4 v[2][4][2]; float ss[2] = {0.f, 0.f};
; #pragma unroll
;         for (int r = 0; r < 2; ++r)
; #pragma unroll
;             for (int j = 0; j < 4; ++j) {
;                 if constexpr (XF32) { const float* xr = (const float*)xin + (size_t)(m0 + r) * D + 8 * lane; v[r][j][0] = *(const f32x4*)(xr + 512 * j); v[r][j][1] = *(const f32x4*)(xr + 512 * j + 4); }
;                 else { float f[8]; unpack8(*(const v4u*)((const bf16*)xin + (size_t)(m0 + r) * D + 8 * lane + 512 * j), f); v[r][j][0] = (f32x4){f[0], f[1], f[2], f[3]}; v[r][j][1] = (f32x4){f[4], f[5], f[6], f[7]}; } }
; #pragma unroll
;         for (int r = 0; r < 2; ++r)
; #pragma unroll
;             for (int j = 0; j < 4; ++j)
; #pragma unroll
;                 for (int e = 0; e < 4; ++e) ss[r] += v[r][j][0][e] * v[r][j][0][e] + v[r][j][1][e] * v[r][j][1][e];
; #pragma unroll
;         for (int r = 0; r < 2; ++r) { const int m = m0 + r, b = m >> 11;
;             const float rstd = rsqrtf(wave_sum(ss[r]) * (1.0f / D) + EPS);
; #pragma unroll
;             for (int j = 0; j < 4; ++j) { const int col = 512 * j + 8 * lane;
; #pragma unroll
;                 for (int q = 0; q < 2; ++q) { const f32x4 gg = *(const f32x4*)(gain + col + 4 * q), s1 = *(const f32x4*)(sc + (size_t)b * MODW + col + 4 * q), s0 = *(const f32x4*)(sh + (size_t)b * MODW + col + 4 * q);
;                     v[r][j][q] = (v[r][j][q] * rstd * gg) * (s1 + 1.0f) + s0; }
.LBB0_940:
	s_ashr_i32 s15, s14, 31
	s_add_i32 s10, s14, 1
	s_lshl_b64 s[12:13], s[14:15], 12
	s_ashr_i32 s11, s10, 31
	v_lshl_add_u64 v[2:3], v[6:7], 0, s[12:13]
	v_lshl_add_u64 v[244:245], v[2:3], 0, s[100:101]
	s_lshl_b64 s[8:9], s[10:11], 12
	global_load_dwordx4 v[20:23], v[2:3], off offset:1024
	global_load_dwordx4 v[24:27], v[2:3], off offset:3072
	global_load_dwordx4 v[34:37], v[2:3], off
	global_load_dwordx4 v[40:43], v[2:3], off offset:2048
	v_lshl_add_u64 v[28:29], v[6:7], 0, s[8:9]
	v_lshl_add_u64 v[246:247], v[28:29], 0, s[100:101]
	global_load_dwordx4 v[80:83], v[28:29], off offset:1024
	global_load_dwordx4 v[94:97], v[28:29], off
	global_load_dwordx4 v[2:5], v[28:29], off offset:3072
	global_load_dwordx4 v[98:101], v[28:29], off offset:2048
	s_ashr_i32 s0, s14, 11
	s_mul_hi_i32 s1, s0, 0xc000
	s_mul_i32 s0, s0, 0xc000
	s_add_u32 s14, s19, s0
	s_addc_u32 s15, s20, s1
	s_add_u32 s16, s7, s0
	s_addc_u32 s17, s18, s1
	v_cmp_lt_i32_e32 vcc, v88, v87
	s_ashr_i32 s0, s10, 11
	s_mul_hi_i32 s1, s0, 0xc000
	v_cndmask_b32_e32 v84, v86, v88, vcc
	v_lshlrev_b32_e32 v84, 2, v84
	v_cmp_lt_i32_e32 vcc, v89, v87
	s_mul_i32 s0, s0, 0xc000
	s_add_u32 s10, s19, s0
	s_addc_u32 s11, s20, s1
	s_waitcnt vmcnt(0)
	v_lshlrev_b32_e32 v47, 16, v22
	v_lshlrev_b32_e32 v45, 16, v20
	v_lshlrev_b32_e32 v59, 16, v36
	v_and_b32_e32 v63, 0xffff0000, v36
	v_lshlrev_b32_e32 v58, 16, v96
	v_and_b32_e32 v62, 0xffff0000, v96
	v_lshlrev_b32_e32 v57, 16, v34
	v_and_b32_e32 v61, 0xffff0000, v34
	v_lshlrev_b32_e32 v65, 16, v37
	v_and_b32_e32 v28, 0xffff0000, v80
	v_and_b32_e32 v32, 0xffff0000, v82
	v_lshlrev_b32_e32 v56, 16, v94
	v_and_b32_e32 v60, 0xffff0000, v94
	v_lshlrev_b32_e32 v64, 16, v97
	v_lshlrev_b32_e32 v44, 16, v80
	v_lshlrev_b32_e32 v46, 16, v82
	v_lshlrev_b32_e32 v48, 16, v81
	v_and_b32_e32 v50, 0xffff0000, v81
	v_lshlrev_b32_e32 v52, 16, v83
	v_and_b32_e32 v54, 0xffff0000, v83
	v_pk_mul_f32 v[80:81], v[58:59], v[58:59]
	v_pk_mul_f32 v[82:83], v[62:63], v[62:63]
	v_lshlrev_b32_e32 v67, 16, v35
	v_and_b32_e32 v71, 0xffff0000, v37
	v_lshlrev_b32_e32 v66, 16, v95
	v_and_b32_e32 v68, 0xffff0000, v95
	v_and_b32_e32 v70, 0xffff0000, v97
	v_pk_mul_f32 v[94:95], v[64:65], v[64:65]
	v_pk_fma_f32 v[80:81], v[56:57], v[56:57], v[80:81]
	v_pk_fma_f32 v[82:83], v[60:61], v[60:61], v[82:83]
	v_and_b32_e32 v69, 0xffff0000, v35
	v_pk_mul_f32 v[96:97], v[70:71], v[70:71]
	v_pk_fma_f32 v[94:95], v[66:67], v[66:67], v[94:95]
	v_pk_add_f32 v[80:81], v[80:81], v[82:83]
	v_pk_fma_f32 v[82:83], v[68:69], v[68:69], v[96:97]
	v_pk_add_f32 v[80:81], v[94:95], v[80:81]
	v_and_b32_e32 v33, 0xffff0000, v22
	v_pk_add_f32 v[80:81], v[82:83], v[80:81]
	v_pk_mul_f32 v[82:83], v[46:47], v[46:47]
	v_and_b32_e32 v29, 0xffff0000, v20
	v_pk_fma_f32 v[82:83], v[44:45], v[44:45], v[82:83]
	v_lshlrev_b32_e32 v53, 16, v23
	v_pk_add_f32 v[80:81], v[82:83], v[80:81]
	v_pk_mul_f32 v[82:83], v[32:33], v[32:33]
	v_lshlrev_b32_e32 v49, 16, v21
	v_pk_fma_f32 v[82:83], v[28:29], v[28:29], v[82:83]
	v_and_b32_e32 v51, 0xffff0000, v21
	v_and_b32_e32 v20, 0xffff0000, v4
	v_lshlrev_b32_e32 v21, 16, v4
	v_pk_add_f32 v[80:81], v[82:83], v[80:81]
	v_pk_mul_f32 v[82:83], v[52:53], v[52:53]
	v_and_b32_e32 v72, 0xffff0000, v24
	v_lshlrev_b32_e32 v73, 16, v24
	v_and_b32_e32 v74, 0xffff0000, v26
	v_lshlrev_b32_e32 v75, 16, v26
	v_and_b32_e32 v55, 0xffff0000, v23
	v_and_b32_e32 v22, 0xffff0000, v2
	v_lshlrev_b32_e32 v23, 16, v2
	v_lshlrev_b32_e32 v24, 16, v98
	v_and_b32_e32 v26, 0xffff0000, v98
	v_lshlrev_b32_e32 v30, 16, v99
	v_and_b32_e32 v34, 0xffff0000, v99
	v_pk_mul_f32 v[98:99], v[20:21], v[20:21]
	v_pk_fma_f32 v[82:83], v[48:49], v[48:49], v[82:83]
	v_pk_fma_f32 v[118:119], v[22:23], v[22:23], v[98:99]
	v_pk_add_f32 v[98:99], v[82:83], v[80:81]
	s_cmp_lg_u32 s24, 0
	s_cbranch_scc1 .Lnorm_once_LBB0_937
	global_load_dwordx4 v[128:131], v1, s[14:15] offset:16
	global_load_dwordx4 v[132:135], v1, s[14:15]
	global_load_dwordx4 v[136:139], v[8:9], off offset:16
	global_load_dwordx4 v[140:143], v[8:9], off
	global_load_dwordx4 v[144:147], v1, s[16:17] offset:16
	global_load_dwordx4 v[148:151], v1, s[16:17]
	global_load_dwordx4 v[152:155], v[10:11], off
	global_load_dwordx4 v[156:159], v1, s[14:15] offset:2048
	global_load_dwordx4 v[160:163], v1, s[16:17] offset:2048
	global_load_dwordx4 v[164:167], v[10:11], off offset:16
	global_load_dwordx4 v[168:171], v1, s[14:15] offset:2064
	global_load_dwordx4 v[172:175], v1, s[16:17] offset:2064
	global_load_dwordx4 v[176:179], v[12:13], off
	global_load_dwordx4 v[180:183], v19, s[14:15]
	global_load_dwordx4 v[184:187], v[12:13], off offset:16
	global_load_dwordx4 v[188:191], v19, s[14:15] offset:16
	global_load_dwordx4 v[192:195], v19, s[16:17]
	global_load_dwordx4 v[196:199], v19, s[16:17] offset:16
	global_load_dwordx4 v[200:203], v[14:15], off
	global_load_dwordx4 v[204:207], v85, s[14:15]
	global_load_dwordx4 v[208:211], v[14:15], off offset:16
	global_load_dwordx4 v[212:215], v85, s[14:15] offset:16
	global_load_dwordx4 v[216:219], v85, s[16:17]
	global_load_dwordx4 v[220:223], v85, s[16:17] offset:16
; template <bool ZP, bool XF32, bool OUT8 = false>
; __device__ __forceinline__ void norm_phase(LAS unsigned char* lds, const void* xin, const float* gain, const float* sh, const float* sc, bf16* hout, const float* wzt, float* zout, int lane, int wave, int vcu, int G) {
;     ...
;                 for (int e = 0; e < 4; ++e) ss[r] += v[r][j][0][e] * v[r][j][0][e] + v[r][j][1][e] * v[r][j][1][e];
; #pragma unroll
;         for (int r = 0; r < 2; ++r) { const int m = m0 + r, b = m >> 11;
;             const float rstd = rsqrtf(wave_sum(ss[r]) * (1.0f / D) + EPS);
; #pragma unroll
;             for (int j = 0; j < 4; ++j) { const int col = 512 * j + 8 * lane;
; #pragma unroll
;                 for (int q = 0; q < 2; ++q) { const f32x4 gg = *(const f32x4*)(gain + col + 4 * q), s1 = *(const f32x4*)(sc + (size_t)b * MODW + col + 4 * q), s0 = *(const f32x4*)(sh + (size_t)b * MODW + col + 4 * q);
.Lnorm_once_LBB0_937:
	v_and_b32_e32 v76, 0xffff0000, v25
	v_lshlrev_b32_e32 v77, 16, v25
	v_and_b32_e32 v78, 0xffff0000, v27
	v_lshlrev_b32_e32 v79, 16, v27
	v_lshlrev_b32_e32 v25, 16, v40
	v_and_b32_e32 v27, 0xffff0000, v40
	v_lshlrev_b32_e32 v37, 16, v42
	v_and_b32_e32 v39, 0xffff0000, v42
	v_lshlrev_b32_e32 v36, 16, v100
	v_and_b32_e32 v38, 0xffff0000, v100
	v_lshlrev_b32_e32 v40, 16, v101
	v_and_b32_e32 v42, 0xffff0000, v101
	v_pk_mul_f32 v[100:101], v[54:55], v[54:55]
	v_lshlrev_b32_e32 v31, 16, v41
	v_pk_fma_f32 v[100:101], v[50:51], v[50:51], v[100:101]
	v_and_b32_e32 v35, 0xffff0000, v41
	v_pk_add_f32 v[98:99], v[100:101], v[98:99]
	v_pk_mul_f32 v[100:101], v[36:37], v[36:37]
	v_lshlrev_b32_e32 v41, 16, v43
	v_pk_fma_f32 v[100:101], v[24:25], v[24:25], v[100:101]
	v_and_b32_e32 v43, 0xffff0000, v43
	v_pk_add_f32 v[98:99], v[100:101], v[98:99]
	v_pk_mul_f32 v[100:101], v[38:39], v[38:39]
	v_pk_mul_f32 v[102:103], v[74:75], v[74:75]
	v_pk_fma_f32 v[100:101], v[26:27], v[26:27], v[100:101]
	v_pk_mul_f32 v[104:105], v[78:79], v[78:79]
	v_pk_add_f32 v[98:99], v[100:101], v[98:99]
	v_pk_mul_f32 v[100:101], v[40:41], v[40:41]
	v_pk_fma_f32 v[114:115], v[72:73], v[72:73], v[102:103]
	v_pk_fma_f32 v[100:101], v[30:31], v[30:31], v[100:101]
	v_pk_fma_f32 v[116:117], v[76:77], v[76:77], v[104:105]
	v_pk_add_f32 v[98:99], v[100:101], v[98:99]
	v_pk_mul_f32 v[100:101], v[42:43], v[42:43]
	v_mov_b32_e32 v122, v119
	v_pk_fma_f32 v[100:101], v[34:35], v[34:35], v[100:101]
	v_mov_b32_e32 v123, v115
	v_pk_add_f32 v[120:121], v[100:101], v[98:99]
	v_and_b32_e32 v4, 0xffff0000, v5
	v_lshlrev_b32_e32 v5, 16, v5
	v_pk_add_f32 v[120:121], v[122:123], v[120:121]
	v_and_b32_e32 v2, 0xffff0000, v3
	v_lshlrev_b32_e32 v3, 16, v3
	v_pk_mul_f32 v[122:123], v[4:5], v[4:5]
	v_mov_b32_e32 v119, v114
	v_pk_fma_f32 v[122:123], v[2:3], v[2:3], v[122:123]
	v_pk_add_f32 v[114:115], v[118:119], v[120:121]
	v_mov_b32_e32 v118, v123
	v_mov_b32_e32 v119, v117
	v_pk_add_f32 v[114:115], v[118:119], v[114:115]
	v_mov_b32_e32 v123, v116
	v_pk_add_f32 v[114:115], v[122:123], v[114:115]
	ds_bpermute_b32 v117, v84, v115
	ds_bpermute_b32 v116, v84, v114
	v_cndmask_b32_e32 v84, v86, v89, vcc
	v_lshlrev_b32_e32 v84, 2, v84
	v_cmp_lt_i32_e32 vcc, v90, v87
	v_mov_b32_e32 v124, v37
	s_waitcnt lgkmcnt(0)
	v_pk_add_f32 v[114:115], v[114:115], v[116:117]
	ds_bpermute_b32 v117, v84, v115
	ds_bpermute_b32 v116, v84, v114
	v_cndmask_b32_e32 v84, v86, v90, vcc
	v_lshlrev_b32_e32 v84, 2, v84
	v_cmp_lt_i32_e32 vcc, v91, v87
	v_mov_b32_e32 v125, v39
	s_waitcnt lgkmcnt(0)
	v_pk_add_f32 v[114:115], v[114:115], v[116:117]
	ds_bpermute_b32 v117, v84, v115
	ds_bpermute_b32 v116, v84, v114
	v_cndmask_b32_e32 v84, v86, v91, vcc
	v_lshlrev_b32_e32 v84, 2, v84
	v_cmp_lt_i32_e32 vcc, v92, v87
	v_mov_b32_e32 v122, v41
	s_waitcnt lgkmcnt(0)
	v_pk_add_f32 v[114:115], v[114:115], v[116:117]
	ds_bpermute_b32 v117, v84, v115
	ds_bpermute_b32 v116, v84, v114
	v_cndmask_b32_e32 v84, v86, v92, vcc
	v_lshlrev_b32_e32 v84, 2, v84
	v_cmp_lt_i32_e32 vcc, v93, v87
	s_waitcnt vmcnt(0)
	v_mov_b64_e32 v[94:95], v[128:129]
	v_mov_b64_e32 v[96:97], v[130:131]
	v_mov_b64_e32 v[80:81], v[132:133]
	v_mov_b64_e32 v[82:83], v[134:135]
	v_mov_b64_e32 v[98:99], v[136:137]
	v_mov_b64_e32 v[100:101], v[138:139]
	v_mov_b64_e32 v[102:103], v[140:141]
	v_mov_b64_e32 v[104:105], v[142:143]
	v_mov_b64_e32 v[106:107], v[144:145]
	v_mov_b64_e32 v[108:109], v[146:147]
	v_mov_b64_e32 v[110:111], v[148:149]
	v_mov_b64_e32 v[112:113], v[150:151]
	s_cmp_lg_u32 s3, 1
	s_cbranch_scc0 .Lnorm_nt_LBB0_937
	global_load_dwordx4 v[248:251], v[244:245], off offset:1024
	global_load_dwordx4 v[248:251], v[244:245], off offset:3072
	global_load_dwordx4 v[248:251], v[244:245], off
	global_load_dwordx4 v[248:251], v[244:245], off offset:2048
	global_load_dwordx4 v[248:251], v[246:247], off offset:1024
	global_load_dwordx4 v[248:251], v[246:247], off
	global_load_dwordx4 v[248:251], v[246:247], off offset:3072
	global_load_dwordx4 v[248:251], v[246:247], off offset:2048
